# v057 SEQ phase: static s_setprio 1 for waves 4-7 (state-update waves)
# baseline (speedup 1.0000x reference)
; #define LAS __attribute__((address_space(3)))
; #define GAS __attribute__((address_space(1)))
;     const int odd = l & 1, nhh = odd ? 4 : 8;
;     ...
;     const GAS bf16_t* P = (const GAS bf16_t*)(F.ws + WS_P); const GAS bf16_t* Q = (const GAS bf16_t*)(F.ws + WS_QKV);
;     ...
;     for (int i = F.tid; i < 32 * 136 / 2; i += NTHREADS) ((LAS unsigned*)(F.lds + SQ_SB))[i] = 0u;
;     if (F.tid < 128) ((LAS float*)(F.lds + SQ_NV))[F.tid] = 0.f;
;     __syncthreads();
;     const Frame F = refresh(F0);
;     const int odd = l & 1; const int nlin = B_ * (odd ? 4 : 8) * 2 * 4; const int ns5 = odd ? B_ * 2 * 32 : 0;
;     const int vcu = (F.G % 8 == 0) ? (F.bid % 8) * (F.G / 8) + F.bid / 8 : F.bid;
;     if (!odd || F.G <= nlin) {
;         for (int it = vcu; it < nlin + ns5; it += F.G) {
;             if (it < nlin) { if (mode != 2) seq_linear_item(F, l, it, mode >= 10 ? mode - 10 : 0); } else if (mode != 1 && mode < 10) seq_s5_item(F, l, it - nlin, 1);
.Lbw4_skip:
	s_waitcnt lgkmcnt(0)
	v_readlane_b32 s100, v251, 29
	s_cmp_lt_u32 s100, 4
	s_cbranch_scc1 .Lseq_prio_lo
	s_setprio 1
.Lseq_prio_lo:
	v_readlane_b32 s38, v255, 61
	s_cmp_lg_u32 s38, 0
	v_readlane_b32 s62, v251, 29
	v_readlane_b32 s4, v251, 0
	s_waitcnt lgkmcnt(0)
	s_barrier
	v_mov_b32_e32 v82, v200
	s_lshl_b32 s0, s62, 6
	v_readlane_b32 s6, v251, 2
	v_readlane_b32 s7, v251, 3
	v_writelane_b32 v254, s0, 27
	v_add_u32_e32 v84, s0, v82
	s_mov_b64 s[2:3], s[6:7]
	v_readlane_b32 s0, v253, 49
	v_readlane_b32 s5, v251, 1
	s_cmp_lg_u32 s0, 0
	v_writelane_b32 v254, s2, 28
	s_cselect_b64 s[4:5], -1, 0
	s_nop 0
	v_writelane_b32 v254, s3, 29
	s_and_b64 s[2:3], s[4:5], exec
	s_cselect_b32 s69, 0x80, s63
	s_lshl_b32 s0, s0, 8
	v_writelane_b32 v254, s0, 30
	s_cmp_gt_i32 s96, s69
	s_cselect_b64 s[2:3], -1, 0
	v_writelane_b32 v254, s4, 31
	s_nop 1
	v_writelane_b32 v254, s5, 32
	s_and_b64 s[4:5], s[4:5], s[2:3]
	s_mov_b64 s[2:3], -1
	s_and_b64 vcc, exec, s[4:5]
	s_cbranch_vccnz .LBB0_1047
	v_writelane_b32 v254, s62, 33
	v_readlane_b32 s68, v253, 11
	v_readlane_b32 s0, v254, 30
	s_add_i32 s83, s69, s0
	v_readlane_b32 s0, v252, 61
	s_cmp_ge_i32 s0, s83
	v_readlane_b32 s67, v253, 12
	s_movk_i32 s62, 0x67f
	s_cbranch_scc1 .LBB0_1046
	v_readlane_b32 s7, v254, 33
	s_mul_i32 s0, s7, 0x3800
	v_readlane_b32 s2, v253, 62
	s_add_i32 s77, s0, 0
	s_and_b32 s0, s2, 2
	v_writelane_b32 v254, s0, 34
	s_lshl_b32 s0, s2, 4
	s_and_b32 s0, s0, 32
	v_writelane_b32 v254, s0, 35
	v_readlane_b32 s3, v253, 63
	v_readlane_b32 s8, v254, 28
	v_readlane_b32 s9, v254, 29
	s_add_u32 s36, s8, 0x415d4c00
	s_addc_u32 s37, s9, 0
	s_add_u32 s0, s8, 0x40d54c00
	v_writelane_b32 v254, s0, 36
	s_addc_u32 s0, s9, 0
	s_cmpk_lt_i32 s7, 0x44
	v_writelane_b32 v254, s0, 37
	s_cselect_b64 s[2:3], -1, 0
	v_writelane_b32 v254, s2, 38
	s_lshl_b32 s6, s72, 1
	s_add_u32 s0, s8, 0x4a655400
	v_writelane_b32 v254, s3, 39
	v_writelane_b32 v254, s0, 40
	s_addc_u32 s0, s9, 0
	v_writelane_b32 v254, s0, 41
	s_add_u32 s0, s8, 0x415d5400
	v_writelane_b32 v254, s0, 42
	s_addc_u32 s0, s9, 0
	s_cmp_gt_i32 s7, 1
	s_cselect_b64 s[40:41], -1, 0
	s_cmp_lt_u32 s7, 4
	s_cselect_b64 s[42:43], -1, 0
	s_cmp_gt_u32 s7, 3
	s_cselect_b64 s[44:45], -1, 0
	s_cmp_gt_u32 s7, 5
	s_cselect_b64 s[46:47], -1, 0
	s_cmp_lg_u32 s7, 6
	v_writelane_b32 v254, s0, 43
	s_cselect_b64 s[2:3], -1, 0
	s_add_u32 s0, s8, 0x60b54c00
	v_writelane_b32 v254, s0, 44
	s_addc_u32 s0, s9, 0
	v_writelane_b32 v254, s0, 45
	s_add_u32 s0, s8, 0x5a554c00
	v_writelane_b32 v254, s0, 46
	s_addc_u32 s0, s9, 0
	v_writelane_b32 v254, s0, 47
	s_add_u32 s0, s8, 0x56154c00
	v_writelane_b32 v254, s0, 8
	s_addc_u32 s0, s9, 0
	v_writelane_b32 v253, s2, 49
	v_writelane_b32 v254, s0, 2
	s_lshl_b32 s0, s7, 3
	v_writelane_b32 v253, s3, 50
	s_sub_i32 s2, s0, 32
	s_lshl_b32 s3, s2, 3
	v_writelane_b32 v254, s3, 6
	s_lshl_b32 s2, s2, 10
	v_writelane_b32 v254, s2, 13
	s_sub_i32 s2, s0, 31
	s_lshl_b32 s3, s2, 3
	v_writelane_b32 v254, s3, 15
	s_lshl_b32 s2, s2, 10
	v_writelane_b32 v254, s2, 17
	s_sub_i32 s2, s0, 30
	s_lshl_b32 s3, s2, 3
	v_writelane_b32 v254, s3, 19
	s_lshl_b32 s2, s2, 10
	v_writelane_b32 v254, s2, 21
	s_sub_i32 s2, s0, 29
	s_lshl_b32 s3, s2, 3
	v_writelane_b32 v254, s3, 23
	s_lshl_b32 s2, s2, 10
	v_writelane_b32 v254, s2, 25
	s_sub_i32 s2, s0, 28
	s_lshl_b32 s3, s2, 3
	s_lshl_b32 s2, s2, 10
	v_writelane_b32 v253, s2, 51
	s_sub_i32 s2, s0, 27
	v_writelane_b32 v254, s3, 11
	s_lshl_b32 s3, s2, 3
	v_writelane_b32 v254, s3, 10
	s_lshl_b32 s2, s2, 10
	v_writelane_b32 v254, s2, 4
	s_sub_i32 s2, s0, 26
	s_lshl_b32 s3, s2, 3
	s_lshl_b32 s2, s2, 10
	v_writelane_b32 v254, s2, 0
	s_sub_i32 s2, s0, 25
	v_writelane_b32 v253, s3, 60
	s_lshl_b32 s3, s2, 3
	s_lshl_b32 s2, s2, 10
	v_writelane_b32 v253, s3, 56
	s_add_u32 s11, s8, 0x51d54c00
	v_writelane_b32 v253, s2, 58
	s_addc_u32 s12, s9, 0
	s_add_i32 s2, s0, -16
	s_lshl_b32 s13, s2, 2
	s_lshl_b32 s22, s2, 10
	s_add_i32 s2, s0, -15
	s_lshl_b32 s23, s2, 2
	s_lshl_b32 s78, s2, 10
	s_add_i32 s2, s0, -14
	s_lshl_b32 s79, s2, 2
	s_lshl_b32 s38, s2, 10
	s_add_i32 s2, s0, -13
	v_cvt_f32_ubyte0_e32 v0, s72
	s_lshl_b32 s39, s2, 2
	s_lshl_b32 s4, s2, 10
	s_add_i32 s2, s0, -12
	v_rcp_iflag_f32_e32 v0, v0
	s_lshl_b32 s5, s2, 2
	s_lshl_b32 s14, s2, 10
	s_add_i32 s2, s0, -11
	s_lshl_b32 s15, s2, 2
	s_lshl_b32 s16, s2, 10
	s_add_i32 s2, s0, -10
	s_lshl_b32 s17, s2, 2
	s_lshl_b32 s33, s2, 10
	s_add_i32 s2, s0, -9
	v_readlane_b32 s10, v254, 27
	s_lshl_b32 s92, s7, 5
	s_lshl_b32 s74, s2, 2
	s_lshl_b32 s30, s2, 10
	s_add_i32 s31, s68, s10
	s_sub_i32 s90, s92, 64
	s_lshl_b32 s91, s7, 11
	s_and_b32 s2, s7, -2
	v_mul_f32_e32 v0, 0x4f7ffffe, v0
	s_cmp_lg_u32 s2, 2
	v_cvt_u32_f32_e32 v0, v0
	s_cselect_b64 s[50:51], -1, 0
	s_cmp_lt_i32 s7, 4
	s_cselect_b64 s[52:53], -1, 0
	s_add_i32 s87, s92, 0xffffff80
	s_lshl_b32 s2, s87, 1
	s_add_i32 s18, s67, s2
	v_readfirstlane_b32 s3, v0
	v_cvt_f32_ubyte0_e32 v0, s6
	s_add_u32 s2, s8, 0x613d4c00
	v_rcp_iflag_f32_e32 v0, v0
	v_writelane_b32 v254, s2, 48
	s_addc_u32 s2, s9, 0
	v_writelane_b32 v254, s2, 49
	s_add_u32 s2, s8, 0x5c754c00
	v_writelane_b32 v254, s2, 50
	s_addc_u32 s2, s9, 0
	s_add_u32 s19, s8, 0x4d954c00
	v_mul_f32_e32 v0, 0x4f7ffffe, v0
	v_writelane_b32 v254, s2, 51
	s_addc_u32 s20, s9, 0
	s_sub_i32 s2, 0, s72
	v_cvt_u32_f32_e32 v0, v0
	s_mul_i32 s2, s2, s3
	s_mul_hi_u32 s2, s3, s2
	s_add_i32 s2, s3, s2
	v_writelane_b32 v254, s2, 52
	s_sub_i32 s2, 0, s6
	v_readfirstlane_b32 s3, v0
	s_mul_i32 s2, s2, s3
	s_mul_hi_u32 s2, s3, s2
	v_writelane_b32 v254, s6, 53
	s_add_i32 s2, s3, s2
	v_writelane_b32 v254, s2, 54
	s_or_b32 s2, s0, 1
	s_lshl_b32 s21, s2, 2
	s_lshl_b32 s76, s2, 10
	s_or_b32 s2, s0, 2
; #define LAUNDER(x) do {} while (0)
; #define LAUNDER_S(x) do {} while (0)
; #define GAS __attribute__((address_space(1)))
; #define LAUNDER(x) asm volatile("" : "+v"(x))
; template <int KIND>
; DEV void seq_dma(const Frame& F, const SeqCtx& C, int n, LAS unsigned char* img) {
;     const int p = C.chain * NCH + n, w = F.wave; int ln = F.lane; LAUNDER(ln);
;     if (w < 2) {
;         if (KIND == 0) { const GAS char* g = (const GAS char*)(F.ws + WS_CLW) + (size_t)p * 16384; LAUNDER_S(g);
; #pragma unroll
;             for (int i = 0; i < 8; ++i) { const int r = 4 * (8 * w + i) + (ln >> 4), pp = ln & 15; glds16(g + r * 256 + 16 * (pp ^ (r & 15)), img + SQ_W + 1024 * (8 * w + i)); } }
;     } else if (w < 4) {
;         const GAS char* g = (const GAS char*)(F.ws + WS_CLQ) + (size_t)p * 16384; LAUNDER_S(g);
; #pragma unroll
;         for (int i = 0; i < 8; ++i) { const int c = 8 * (w - 2) + i, r = 4 * c + (ln >> 4), pp = ln & 15; glds16(g + r * 256 + 16 * (pp ^ (r & 15)), img + SQ_Q + 1024 * c); }
;     } else if (w < 6) {
;         const GAS char* g = (const GAS char*)(F.ws + WS_CLK) + (size_t)p * 16384; LAUNDER_S(g);
; #pragma unroll
;         for (int i = 0; i < 8; ++i) { const int c = 8 * (w - 4) + i, r = 8 * c + (ln >> 3), pp = ln & 7; glds16(g + r * 128 + 16 * (pp ^ ((r >> 1) & 7)), img + SQ_K + 1024 * c); }
;     } else if (w == 6) {
;         const GAS char* g = (const GAS char*)(F.ws + WS_CLA) + (size_t)p * 8192; LAUNDER_S(g);
; #pragma unroll
;         for (int i = 0; i < 8; ++i) { const int r = 8 * i + (ln >> 3), pp = ln & 7; glds16(g + r * 128 + 16 * (pp ^ ((r >> 1) & 7)), img + SQ_A + 1024 * i); }
;     } else {
;     ...
; #pragma unroll
;             for (int i = 0; i < 4; ++i) { const int r = 16 * i + (ln >> 2); glds16(g + r * 256 + 16 * (ln & 3), img + SQ_U + 1024 * i); }
;         } else { const int r0 = tok_row(C.b, C.d, n * 64); const long st = C.d ? -(long)C.vld * 2 : (long)C.vld * 2;
;             const GAS char* g = (const GAS char*)C.vsrc + (long)r0 * C.vld * 2 + 64 * C.sl; LAUNDER_S(g);
; #pragma unroll
;             for (int i = 0; i < 4; ++i) { const int r = 16 * i + (ln >> 2); glds16(g + (long)r * st + 16 * (ln & 3), img + SQ_U + 1024 * i); }
;         }
;         const GAS char* cs = (const GAS char*)(F.ws + WS_CLS) + (size_t)p * 2048; LAUNDER_S(cs);
;         glds16(cs + 16 * ln, img + SQ_C);
	s_lshl_b32 s73, s2, 2
	s_lshl_b32 s75, s2, 10
	s_or_b32 s2, s0, 3
	s_lshl_b32 s82, s2, 2
	s_lshl_b32 s48, s2, 10
	s_or_b32 s2, s0, 4
	s_lshl_b32 s49, s2, 2
	s_lshl_b32 s93, s2, 10
	s_or_b32 s2, s0, 5
	s_lshl_b32 s94, s2, 2
	s_lshl_b32 s95, s2, 10
	s_or_b32 s2, s0, 6
	s_or_b32 s0, s0, 7
	s_lshl_b32 s80, s0, 2
	s_lshl_b32 s81, s0, 10
	s_lshl_b32 s0, s90, 2
	v_readlane_b32 s6, v253, 13
	s_add_i32 s0, s6, s0
	s_lshl_b32 s96, s2, 2
	s_lshl_b32 s97, s2, 10
	v_writelane_b32 v253, s0, 55
	s_lshl_b32 s85, s7, 13
	v_readlane_b32 s0, v252, 62
	s_add_u32 s0, s8, s0
	v_readlane_b32 s2, v252, 63
	s_addc_u32 s2, s9, s2
	s_mul_i32 s3, s69, 0xffff7800
	v_ashrrev_i32_e32 v6, 4, v82
	s_add_u32 s54, s0, s3
	s_mul_hi_i32 s0, s69, 0xffff7800
	v_ashrrev_i32_e32 v83, 31, v82
	v_lshlrev_b32_e32 v92, 3, v6
	s_addc_u32 s55, s2, s0
	v_lshl_add_u64 v[2:3], v[82:83], 2, s[8:9]
	s_mov_b64 s[2:3], 0x32bc8000
	v_ashrrev_i32_e32 v93, 31, v92
	v_and_b32_e32 v86, 15, v82
	v_lshl_add_u64 v[88:89], v[2:3], 0, s[2:3]
	v_lshlrev_b64 v[2:3], 1, v[92:93]
	v_lshl_add_u64 v[4:5], s[8:9], 0, v[2:3]
	s_mov_b64 s[2:3], 0x32bd8000
	v_lshlrev_b32_e32 v0, 8, v86
	v_lshl_add_u64 v[94:95], v[4:5], 0, s[2:3]
	v_lshl_add_u64 v[4:5], s[8:9], 0, v[0:1]
	v_lshl_add_u64 v[2:3], v[4:5], 0, v[2:3]
	v_add_u32_e32 v5, 0xffffff00, v84
	v_and_b32_e32 v7, 3, v82
	s_lshl_b32 s0, s7, 9
	v_ashrrev_i32_e32 v160, 2, v5
	v_lshlrev_b32_e32 v8, 2, v7
	v_lshlrev_b32_e32 v87, 2, v82
	s_add_i32 s0, s0, 0
	s_mov_b64 s[2:3], 0x32c58000
	v_bitop3_b32 v10, v160, v8, 15 bitop3:0x6c
	v_add_u32_e32 v91, s0, v87
	v_lshl_add_u64 v[96:97], v[2:3], 0, s[2:3]
	v_mov_b32_e32 v3, s77
	s_movk_i32 s0, 0x50
	v_lshlrev_b32_e32 v162, 4, v10
	v_or_b32_e32 v10, 1, v8
	v_mad_u32_u24 v3, v86, s0, v3
	v_mul_lo_u32 v4, v82, s0
	v_readlane_b32 s0, v253, 10
	v_bitop3_b32 v10, v160, v10, 15 bitop3:0x6c
	v_lshlrev_b32_e32 v163, 4, v10
	v_lshl_add_u32 v159, v84, 2, s0
	v_or_b32_e32 v10, 2, v8
	s_sub_i32 s0, 0, s10
	v_bitop3_b32 v10, v160, v10, 15 bitop3:0x6c
	v_and_b32_e32 v5, -4, v5
	v_writelane_b32 v254, s0, 55
	s_movk_i32 s0, 0x2200
	v_lshlrev_b32_e32 v164, 4, v10
	v_add_u32_e32 v166, s6, v5
	v_lshl_add_u32 v10, s7, 8, v87
	v_cmp_gt_i32_e64 s[6:7], s0, v84
	v_or_b32_e32 v110, s10, v86
	v_or_b32_e32 v114, 16, v110
	v_writelane_b32 v254, s6, 56
	v_or_b32_e32 v118, 32, v110
	v_or_b32_e32 v122, 48, v110
	v_writelane_b32 v254, s7, 57
	v_cmp_gt_i32_e64 s[6:7], s63, v110
	s_movk_i32 s0, 0x880
	v_max_i32_e32 v5, 0x2000, v84
	v_writelane_b32 v254, s6, 58
	v_or_b32_e32 v8, 3, v8
	v_sub_u32_e32 v5, v5, v84
	v_writelane_b32 v254, s7, 59
	v_cmp_gt_i32_e64 s[6:7], s63, v114
	v_bitop3_b32 v8, v160, v8, 15 bitop3:0x6c
	v_add_u32_e32 v5, 0x1ff, v5
	v_writelane_b32 v254, s6, 60
	v_lshlrev_b32_e32 v165, 4, v8
	v_lshrrev_b32_e32 v8, 9, v5
	v_writelane_b32 v254, s7, 61
	v_cmp_gt_i32_e64 s[6:7], s63, v118
	v_add_u32_e32 v8, 1, v8
	v_and_b32_e32 v168, 0xfffffe, v8
	v_writelane_b32 v254, s6, 62
	v_and_b32_e32 v2, -16, v82
	v_add_u32_e32 v0, s77, v0
	v_writelane_b32 v254, s7, 63
	v_cmp_gt_i32_e64 s[6:7], s63, v122
	v_lshlrev_b32_e32 v83, 2, v6
	v_lshlrev_b32_e32 v9, 7, v7
	v_writelane_b32 v255, s6, 0
	v_or_b32_e32 v127, 1, v83
	v_or_b32_e32 v129, 2, v83
	v_writelane_b32 v255, s7, 1
	v_cmp_gt_i32_e64 s[6:7], s0, v84
	s_movk_i32 s0, 0x80
	v_or_b32_e32 v131, 3, v83
	v_writelane_b32 v255, s6, 2
	v_add_u32_e32 v175, v0, v2
	v_add_u32_e32 v0, 0, v9
	v_writelane_b32 v255, s7, 3
	v_cmp_gt_i32_e64 s[6:7], s0, v84
	s_movk_i32 s0, 0x180
	v_lshlrev_b32_e32 v90, 4, v86
	v_writelane_b32 v255, s6, 4
	v_add_u32_e32 v111, 0xffffff00, v110
	v_sub_u32_e32 v112, 0x10ff, v110
	v_writelane_b32 v255, s7, 5
	v_cmp_eq_u32_e64 s[6:7], 0, v7
	v_sub_u32_e32 v113, 0xff, v110
	v_add_u32_e32 v115, 0xffffff10, v110
	v_writelane_b32 v255, s6, 6
	v_sub_u32_e32 v116, 0x10ff, v114
	v_sub_u32_e32 v117, 0xff, v114
	v_writelane_b32 v255, s7, 7
	v_cmp_gt_i32_e64 s[6:7], s0, v84
	s_movk_i32 s0, 0x1ff
	v_add_u32_e32 v119, 0xffffff20, v110
	v_writelane_b32 v255, s6, 8
	v_sub_u32_e32 v120, 0x10ff, v118
	v_sub_u32_e32 v121, 0xff, v118
	v_writelane_b32 v255, s7, 9
	v_cmp_lt_u32_e64 s[6:7], s0, v5
	v_add_u32_e32 v123, 0xffffff30, v110
	v_sub_u32_e32 v124, 0x10ff, v122
	v_writelane_b32 v255, s6, 10
	v_sub_u32_e32 v125, 0xff, v122
	v_sub_u32_e32 v126, 0, v83
	v_writelane_b32 v255, s7, 11
	v_cmp_ne_u32_e64 s[6:7], v8, v168
	v_sub_u32_e32 v128, 0, v127
	v_sub_u32_e32 v130, 0, v129
	v_writelane_b32 v255, s6, 12
	v_sub_u32_e32 v132, 0, v131
	v_add_u32_e32 v133, 16, v83
	v_writelane_b32 v255, s7, 13
	v_writelane_b32 v255, s69, 14
	v_sub_u32_e32 v134, -16, v83
	v_add_u32_e32 v135, 17, v83
	v_sub_u32_e32 v136, 0xffffffef, v83
	v_add_u32_e32 v137, 18, v83
	v_sub_u32_e32 v138, 0xffffffee, v83
	v_add_u32_e32 v139, 19, v83
	v_sub_u32_e32 v140, 0xffffffed, v83
	v_add_u32_e32 v141, 32, v83
	v_sub_u32_e32 v142, 0xffffffe0, v83
	v_add_u32_e32 v143, 33, v83
	v_sub_u32_e32 v144, 0xffffffdf, v83
	v_add_u32_e32 v145, 34, v83
	v_sub_u32_e32 v147, 0xffffffde, v83
	v_add_u32_e32 v148, 35, v83
	v_sub_u32_e32 v150, 0xffffffdd, v83
	v_add_u32_e32 v151, 48, v83
	v_sub_u32_e32 v152, 0xffffffd0, v83
	v_add_u32_e32 v153, 49, v83
	v_sub_u32_e32 v154, 0xffffffcf, v83
	v_add_u32_e32 v155, 50, v83
	v_sub_u32_e32 v156, 0xffffffce, v83
	v_add_u32_e32 v157, 51, v83
	v_sub_u32_e32 v158, 0xffffffcd, v83
	v_lshlrev_b32_e32 v161, 8, v160
	v_add_u32_e32 v167, 0xfffffc00, v159
	v_lshl_add_u32 v169, v168, 9, v84
	v_add_u32_e32 v85, 0x200, v84
	v_add_u32_e32 v170, 0, v10
	v_add_u32_e32 v171, 0xfffffe00, v84
	v_add_u32_e32 v172, s67, v10
	v_add_u32_e32 v173, v3, v2
	v_add_u32_e32 v174, s77, v4
	v_add_u32_e32 v176, 0x24400, v0
	v_readlane_b32 s86, v252, 61
	v_cmp_gt_i32_e64 s[2:3], 2, v6
	v_writelane_b32 v255, s83, 15
	s_branch .LBB0_817

; #define WAIT_VM(n) do {} while (0)
; #define WAIT_ALL() do {} while (0)
; #define LAUNDER_S(x) do {} while (0)
; #define WAIT_VM(n) asm volatile("s_waitcnt vmcnt(" #n ")" ::: "memory")
; #define WAIT_ALL() asm volatile("s_waitcnt vmcnt(0) lgkmcnt(0)" ::: "memory")
; #define LAUNDER_S(x) asm volatile("" : "+s"(x))
; DEV int lane_id() { return (int)__builtin_amdgcn_mbcnt_hi(~0u, __builtin_amdgcn_mbcnt_lo(~0u, 0u)); }
; DEV unsigned xb_add(unsigned* p, unsigned v) { return __hip_atomic_fetch_add(p, v, __ATOMIC_RELAXED, __HIP_MEMORY_SCOPE_AGENT); }
; DEV void xcd_barrier(const XcdBarrier& b) {
;     WAIT_VM(0);
;     __syncthreads();
;     int bw = b.wave; LAUNDER_S(bw);
;     if (bw == 0 && lane_id() == 0) {
;         unsigned* bar = b.bar; LAUNDER_S(bar);
;         unsigned bx = b.x; LAUNDER_S(bx);
;         WAIT_ALL();
;         unsigned nloc = b.st[0], nx = b.st[1];
;         if (nloc == 0u) { xcd_barrier_complete(bar, bx, nloc, nx); b.st[0] = nloc; b.st[1] = nx; }
;         const unsigned old = xb_add(&bar[XB_XSUB(bx)], 1u);
;         const unsigned gen = old / nloc;
;         if (old + 1u == (gen + 1u) * nloc) {
;     ...
;     if (!odd || F.G <= nlin) {
;         for (int it = vcu; it < nlin + ns5; it += F.G) {
;             if (it < nlin) { if (mode != 2) seq_linear_item(F, l, it, mode >= 10 ? mode - 10 : 0); } else if (mode != 1 && mode < 10) seq_s5_item(F, l, it - nlin, 1);
;             __syncthreads();
;         }
;     } else if (vcu < nlin) { if (mode != 2) seq_linear_item(F, l, vcu, mode >= 10 ? mode - 10 : 0); }
;     else { for (int it = vcu - nlin; it < ns5; it += F.G - nlin) { if (mode != 1 && mode < 10) seq_s5_item(F, l, it, 1); __syncthreads(); } }
; }
.LBB0_1158:
	s_setprio 0
	s_waitcnt vmcnt(0)
	v_readlane_b32 s0, v251, 29
	s_waitcnt vmcnt(0) lgkmcnt(0)
	s_barrier
	s_nop 0
	v_or_b32_e32 v0, s0, v200
	v_cmp_eq_u32_e32 vcc, 0, v0
	s_and_saveexec_b64 s[34:35], vcc
	s_cbranch_execz .LBB0_1202
	v_readlane_b32 s4, v251, 0
	v_readlane_b32 s6, v251, 2
	v_readlane_b32 s7, v251, 3
	s_mov_b64 s[36:37], s[6:7]
	v_readlane_b32 s0, v251, 28
	v_readlane_b32 s2, v253, 7
	s_waitcnt vmcnt(0) lgkmcnt(0)
	v_readlane_b32 s5, v251, 1
	s_nop 0
	v_mov_b32_e32 v0, s2
	ds_read_b32 v2, v0
	v_readlane_b32 s2, v253, 8
	s_waitcnt lgkmcnt(0)
	v_cmp_ne_u32_e32 vcc, 0, v2
	v_mov_b32_e32 v0, s2
	ds_read_b32 v0, v0
	s_cbranch_vccnz .LBB0_1173
	s_add_u32 s2, s36, 0x1000
	s_addc_u32 s3, s37, 0
	s_add_u32 s4, s36, 0x1100
	s_addc_u32 s5, s37, 0
	s_add_u32 s6, s36, 0x1200
	s_addc_u32 s7, s37, 0
	s_add_u32 s8, s36, 0x1300
	s_addc_u32 s9, s37, 0
	s_mov_b32 s28, 1
	s_mov_b64 s[10:11], 0
	s_branch .LBB0_1163
